# prep_a_prompt layernorm stats: the 32 wave sums per unit done with DPP row_shr/row_bcast adds + v_readlane instead of 6 serialized ds_bpermute round trips each
# speedup vs baseline: 1.0011x; 1.0011x over previous
; DI float sigm(float x) { return __builtin_amdgcn_rcpf(1.f + __expf(-x)); }
; DI float gelu_t(float x) { return x * sigm(1.5957691216057308f * (x + 0.044715f * x * x * x)); }
; DI float silu_(float x) { return x * sigm(x); }
; DI float softplus_(float x) { return fmaxf(x, 0.f) + log1pf(__expf(-fabsf(x))); }
; DI float wsum(float v) {
; #pragma unroll
;     for (int o = 32; o >= 1; o >>= 1) v += __shfl_xor(v, o, 64);
;     return v;
; DI void prep_a_prompt(LAS unsigned char* lds, const Params& P, int l, int unit) {
;     ...
; #pragma unroll 8
;     for (int i = 0; i < 16; ++i) { const int t = wave * 16 + i; const float* p = P32 + (size_t)(row0 + t) * LDP + C_AV + lane * 8;
;         const f32x4 a = *(const f32x4*)p, bq = *(const f32x4*)(p + 4); float x[8];
; #pragma unroll
;         for (int e = 0; e < 4; ++e) { x[e] = gelu_t(a[e]); x[4 + e] = gelu_t(bq[e]); }
;         float s = 0.f;
; #pragma unroll
;         for (int e = 0; e < 8; ++e) s += x[e];
;         const float mean = wsum(s) * (1.f / 512.f); float d = 0.f;
; #pragma unroll
;         for (int e = 0; e < 8; ++e) d += (x[e] - mean) * (x[e] - mean);
;         const float var = wsum(d) * (1.f / 512.f);
;         if (lane == 0) { st[t * 2] = mean; st[t * 2 + 1] = rsqrtf(var + 1e-6f); } }
.LBB0_752:
	v_lshl_add_u64 v[4:5], v[2:3], 0, s[54:55]
	s_mov_b32 s11, 0
	s_mov_b32 s10, 0x0
	v_lshl_add_u64 v[120:121], v[4:5], 0, s[10:11]
	global_load_dwordx4 v[56:59], v[120:121], off offset:2048
	global_load_dwordx4 v[60:63], v[120:121], off offset:2064
	s_mov_b32 s10, 0x6800
	v_lshl_add_u64 v[120:121], v[4:5], 0, s[10:11]
	global_load_dwordx4 v[64:67], v[120:121], off offset:2048
	global_load_dwordx4 v[68:71], v[120:121], off offset:2064
	s_mov_b32 s10, 0xd000
	v_lshl_add_u64 v[120:121], v[4:5], 0, s[10:11]
	global_load_dwordx4 v[72:75], v[120:121], off offset:2048
	global_load_dwordx4 v[76:79], v[120:121], off offset:2064
	s_mov_b32 s10, 0x13800
	v_lshl_add_u64 v[120:121], v[4:5], 0, s[10:11]
	global_load_dwordx4 v[80:83], v[120:121], off offset:2048
	global_load_dwordx4 v[84:87], v[120:121], off offset:2064
	s_mov_b32 s10, 0x1a000
	v_lshl_add_u64 v[120:121], v[4:5], 0, s[10:11]
	global_load_dwordx4 v[88:91], v[120:121], off offset:2048
	global_load_dwordx4 v[92:95], v[120:121], off offset:2064
	s_mov_b32 s10, 0x20800
	v_lshl_add_u64 v[120:121], v[4:5], 0, s[10:11]
	global_load_dwordx4 v[96:99], v[120:121], off offset:2048
	global_load_dwordx4 v[100:103], v[120:121], off offset:2064
	s_mov_b32 s10, 0x27000
	v_lshl_add_u64 v[120:121], v[4:5], 0, s[10:11]
	global_load_dwordx4 v[104:107], v[120:121], off offset:2048
	global_load_dwordx4 v[108:111], v[120:121], off offset:2064
	s_mov_b32 s10, 0x2d800
	v_lshl_add_u64 v[120:121], v[4:5], 0, s[10:11]
	global_load_dwordx4 v[112:115], v[120:121], off offset:2048
	global_load_dwordx4 v[116:119], v[120:121], off offset:2064
	s_waitcnt vmcnt(15) lgkmcnt(0)
	v_mov_b32_e32 v18, v56
	v_mov_b32_e32 v19, v57
	v_mov_b32_e32 v20, v58
	v_mov_b32_e32 v21, v59
	v_mul_f32_e32 v6, 0x3d372713, v18
	v_mul_f32_e32 v26, 0x3d372713, v19
	v_mul_f32_e32 v6, v18, v6
	v_mul_f32_e32 v28, 0x3d372713, v20
	v_mul_f32_e32 v26, v19, v26
	v_fma_f32 v6, v18, v6, v18
	v_mul_f32_e32 v30, 0x3d372713, v21
	v_mul_f32_e32 v28, v20, v28
	v_fma_f32 v26, v19, v26, v19
	v_mul_f32_e32 v6, 0x3fcc422a, v6
	s_waitcnt vmcnt(14)
	v_mov_b32_e32 v22, v60
	v_mov_b32_e32 v23, v61
	v_mov_b32_e32 v24, v62
	v_mov_b32_e32 v25, v63
	v_mul_f32_e32 v7, 0x3d372713, v22
	v_mul_f32_e32 v30, v21, v30
	v_fma_f32 v28, v20, v28, v20
	v_mul_f32_e32 v26, 0x3fcc422a, v26
	v_mul_f32_e32 v6, 0xbfb8aa3b, v6
	v_mul_f32_e32 v27, 0x3d372713, v23
	v_mul_f32_e32 v7, v22, v7
	v_fma_f32 v30, v21, v30, v21
	v_mul_f32_e32 v28, 0x3fcc422a, v28
	v_mul_f32_e32 v26, 0xbfb8aa3b, v26
	v_exp_f32_e32 v6, v6
	v_mul_f32_e32 v29, 0x3d372713, v24
	v_mul_f32_e32 v27, v23, v27
	v_fma_f32 v7, v22, v7, v22
	v_mul_f32_e32 v30, 0x3fcc422a, v30
	v_mul_f32_e32 v28, 0xbfb8aa3b, v28
	v_exp_f32_e32 v26, v26
	v_mul_f32_e32 v31, 0x3d372713, v25
	v_mul_f32_e32 v29, v24, v29
	v_fma_f32 v27, v23, v27, v23
	v_mul_f32_e32 v7, 0x3fcc422a, v7
	v_mul_f32_e32 v30, 0xbfb8aa3b, v30
	v_exp_f32_e32 v28, v28
	v_mul_f32_e32 v31, v25, v31
	v_fma_f32 v29, v24, v29, v24
	v_mul_f32_e32 v27, 0x3fcc422a, v27
	v_mul_f32_e32 v7, 0xbfb8aa3b, v7
	v_exp_f32_e32 v30, v30
	v_fma_f32 v31, v25, v31, v25
	v_mul_f32_e32 v29, 0x3fcc422a, v29
	v_mul_f32_e32 v27, 0xbfb8aa3b, v27
	v_exp_f32_e32 v7, v7
	v_add_f32_e32 v6, 1.0, v6
	v_mul_f32_e32 v31, 0x3fcc422a, v31
	v_mul_f32_e32 v29, 0xbfb8aa3b, v29
	v_exp_f32_e32 v27, v27
	v_add_f32_e32 v26, 1.0, v26
	v_rcp_f32_e32 v32, v6
	v_mul_f32_e32 v31, 0xbfb8aa3b, v31
	v_exp_f32_e32 v29, v29
	v_add_f32_e32 v28, 1.0, v28
	v_rcp_f32_e32 v26, v26
	v_exp_f32_e32 v31, v31
	v_add_f32_e32 v30, 1.0, v30
	v_rcp_f32_e32 v28, v28
	v_add_f32_e32 v7, 1.0, v7
	v_rcp_f32_e32 v30, v30
	v_add_f32_e32 v27, 1.0, v27
	v_rcp_f32_e32 v7, v7
	v_fma_f32 v6, v18, v32, 0
	v_add_f32_e32 v29, 1.0, v29
	v_rcp_f32_e32 v27, v27
	v_fmac_f32_e32 v6, v19, v26
	v_add_f32_e32 v31, 1.0, v31
	v_rcp_f32_e32 v29, v29
	v_fmac_f32_e32 v6, v20, v28
	v_rcp_f32_e32 v31, v31
	v_fmac_f32_e32 v6, v21, v30
	v_fmac_f32_e32 v6, v22, v7
	v_fmac_f32_e32 v6, v23, v27
	v_fmac_f32_e32 v6, v24, v29
	v_fmac_f32_e32 v6, v25, v31
	s_nop 1
	v_add_f32_dpp v6, v6, v6 row_shr:1 row_mask:0xf bank_mask:0xf bound_ctrl:0
	s_nop 1
	v_add_f32_dpp v6, v6, v6 row_shr:2 row_mask:0xf bank_mask:0xf bound_ctrl:0
	s_nop 1
	v_add_f32_dpp v6, v6, v6 row_shr:4 row_mask:0xf bank_mask:0xf bound_ctrl:0
	s_nop 1
	v_add_f32_dpp v6, v6, v6 row_shr:8 row_mask:0xf bank_mask:0xf bound_ctrl:0
	s_nop 1
	v_add_f32_dpp v6, v6, v6 row_bcast:15 row_mask:0xa bank_mask:0xf
	s_nop 1
	v_add_f32_dpp v6, v6, v6 row_bcast:31 row_mask:0xc bank_mask:0xf
	s_nop 1
	v_readlane_b32 s10, v6, 63
	s_nop 1
	v_mov_b32_e32 v6, s10
	v_mul_f32_e32 v6, 0x3b000000, v6
	v_fma_f32 v19, v19, v26, -v6
	v_fma_f32 v18, v18, v32, -v6
	v_mul_f32_e32 v19, v19, v19
	v_fma_f32 v20, v20, v28, -v6
	v_fmac_f32_e32 v19, v18, v18
	v_fma_f32 v21, v21, v30, -v6
	v_fmac_f32_e32 v19, v20, v20
	v_fma_f32 v7, v22, v7, -v6
	v_fmac_f32_e32 v19, v21, v21
	v_fma_f32 v22, v23, v27, -v6
	v_fmac_f32_e32 v19, v7, v7
	v_fma_f32 v23, v24, v29, -v6
	v_fmac_f32_e32 v19, v22, v22
	v_fmac_f32_e32 v19, v23, v23
	v_fma_f32 v7, v25, v31, -v6
	v_fmac_f32_e32 v19, v7, v7
	v_mov_b32_e32 v7, v19
	s_nop 1
	v_add_f32_dpp v7, v7, v7 row_shr:1 row_mask:0xf bank_mask:0xf bound_ctrl:0
	s_nop 1
	v_add_f32_dpp v7, v7, v7 row_shr:2 row_mask:0xf bank_mask:0xf bound_ctrl:0
	s_nop 1
	v_add_f32_dpp v7, v7, v7 row_shr:4 row_mask:0xf bank_mask:0xf bound_ctrl:0
	s_nop 1
	v_add_f32_dpp v7, v7, v7 row_shr:8 row_mask:0xf bank_mask:0xf bound_ctrl:0
	s_nop 1
	v_add_f32_dpp v7, v7, v7 row_bcast:15 row_mask:0xa bank_mask:0xf
	s_nop 1
	v_add_f32_dpp v7, v7, v7 row_bcast:31 row_mask:0xc bank_mask:0xf
	s_nop 1
	v_readlane_b32 s10, v7, 63
	s_nop 1
	v_mov_b32_e32 v7, s10
	v_mov_b32_e32 v18, 0
	s_and_saveexec_b64 s[56:57], s[42:43]
	s_cbranch_execz .LBB0_754
	s_waitcnt lgkmcnt(0)
	v_add_f32_e32 v7, v7, v18
	v_fmamk_f32 v7, v7, 0x3b000000, v194
	v_mul_f32_e32 v18, 0x4b800000, v7
	v_cmp_gt_f32_e32 vcc, s95, v7
	s_nop 1
	v_cndmask_b32_e32 v7, v7, v18, vcc
	v_rsq_f32_e32 v7, v7
	s_nop 0
	v_mul_f32_e32 v18, 0x45800000, v7
	v_cndmask_b32_e32 v7, v7, v18, vcc
	ds_write_b64 v17, v[6:7]
; DI float sigm(float x) { return __builtin_amdgcn_rcpf(1.f + __expf(-x)); }
; DI float gelu_t(float x) { return x * sigm(1.5957691216057308f * (x + 0.044715f * x * x * x)); }
; DI float silu_(float x) { return x * sigm(x); }
; DI float softplus_(float x) { return fmaxf(x, 0.f) + log1pf(__expf(-fabsf(x))); }
; DI float wsum(float v) {
; #pragma unroll
;     for (int o = 32; o >= 1; o >>= 1) v += __shfl_xor(v, o, 64);
;     return v;
; DI void prep_a_prompt(LAS unsigned char* lds, const Params& P, int l, int unit) {
;     ...
; #pragma unroll 8
;     for (int i = 0; i < 16; ++i) { const int t = wave * 16 + i; const float* p = P32 + (size_t)(row0 + t) * LDP + C_AV + lane * 8;
;         const f32x4 a = *(const f32x4*)p, bq = *(const f32x4*)(p + 4); float x[8];
; #pragma unroll
;         for (int e = 0; e < 4; ++e) { x[e] = gelu_t(a[e]); x[4 + e] = gelu_t(bq[e]); }
;         float s = 0.f;
; #pragma unroll
;         for (int e = 0; e < 8; ++e) s += x[e];
;         const float mean = wsum(s) * (1.f / 512.f); float d = 0.f;
; #pragma unroll
;         for (int e = 0; e < 8; ++e) d += (x[e] - mean) * (x[e] - mean);
;         const float var = wsum(d) * (1.f / 512.f);
;         if (lane == 0) { st[t * 2] = mean; st[t * 2 + 1] = rsqrtf(var + 1e-6f); } }
.LBB0_754:
	s_or_b64 exec, exec, s[56:57]
	s_waitcnt lgkmcnt(0)
	v_add_co_u32_e32 v18, vcc, 0x7000, v4
	s_mov_b64 s[6:7], 0x7000
	s_nop 0
	v_addc_co_u32_e32 v19, vcc, 0, v5, vcc
	v_lshl_add_u64 v[6:7], v[4:5], 0, s[6:7]
	s_nop 0
	s_waitcnt vmcnt(13)
	v_mov_b32_e32 v18, v64
	v_mov_b32_e32 v19, v65
	v_mov_b32_e32 v20, v66
	v_mov_b32_e32 v21, v67
	v_mul_f32_e32 v6, 0x3d372713, v18
	v_mul_f32_e32 v26, 0x3d372713, v19
	v_mul_f32_e32 v6, v18, v6
	v_mul_f32_e32 v28, 0x3d372713, v20
	v_mul_f32_e32 v26, v19, v26
	v_fma_f32 v6, v18, v6, v18
	v_mul_f32_e32 v30, 0x3d372713, v21
	v_mul_f32_e32 v28, v20, v28
	v_fma_f32 v26, v19, v26, v19
	v_mul_f32_e32 v6, 0x3fcc422a, v6
	s_waitcnt vmcnt(12)
	v_mov_b32_e32 v22, v68
	v_mov_b32_e32 v23, v69
	v_mov_b32_e32 v24, v70
	v_mov_b32_e32 v25, v71
	v_mul_f32_e32 v7, 0x3d372713, v22
	v_mul_f32_e32 v30, v21, v30
	v_fma_f32 v28, v20, v28, v20
	v_mul_f32_e32 v26, 0x3fcc422a, v26
	v_mul_f32_e32 v6, 0xbfb8aa3b, v6
	v_mul_f32_e32 v27, 0x3d372713, v23
	v_mul_f32_e32 v7, v22, v7
	v_fma_f32 v30, v21, v30, v21
	v_mul_f32_e32 v28, 0x3fcc422a, v28
	v_mul_f32_e32 v26, 0xbfb8aa3b, v26
	v_exp_f32_e32 v6, v6
	v_mul_f32_e32 v29, 0x3d372713, v24
	v_mul_f32_e32 v27, v23, v27
	v_fma_f32 v7, v22, v7, v22
	v_mul_f32_e32 v30, 0x3fcc422a, v30
	v_mul_f32_e32 v28, 0xbfb8aa3b, v28
	v_exp_f32_e32 v26, v26
	v_mul_f32_e32 v31, 0x3d372713, v25
	v_mul_f32_e32 v29, v24, v29
	v_fma_f32 v27, v23, v27, v23
	v_mul_f32_e32 v7, 0x3fcc422a, v7
	v_mul_f32_e32 v30, 0xbfb8aa3b, v30
	v_exp_f32_e32 v28, v28
	v_mul_f32_e32 v31, v25, v31
	v_fma_f32 v29, v24, v29, v24
	v_mul_f32_e32 v27, 0x3fcc422a, v27
	v_mul_f32_e32 v7, 0xbfb8aa3b, v7
	v_exp_f32_e32 v30, v30
	v_fma_f32 v31, v25, v31, v25
	v_mul_f32_e32 v29, 0x3fcc422a, v29
	v_mul_f32_e32 v27, 0xbfb8aa3b, v27
	v_exp_f32_e32 v7, v7
	v_add_f32_e32 v6, 1.0, v6
	v_mul_f32_e32 v31, 0x3fcc422a, v31
	v_mul_f32_e32 v29, 0xbfb8aa3b, v29
	v_exp_f32_e32 v27, v27
	v_add_f32_e32 v26, 1.0, v26
	v_rcp_f32_e32 v32, v6
	v_mul_f32_e32 v31, 0xbfb8aa3b, v31
	v_exp_f32_e32 v29, v29
	v_add_f32_e32 v28, 1.0, v28
	v_rcp_f32_e32 v26, v26
	v_exp_f32_e32 v31, v31
	v_add_f32_e32 v30, 1.0, v30
	v_rcp_f32_e32 v28, v28
	v_add_f32_e32 v7, 1.0, v7
	v_rcp_f32_e32 v30, v30
	v_add_f32_e32 v27, 1.0, v27
	v_rcp_f32_e32 v7, v7
	v_fma_f32 v6, v18, v32, 0
	v_add_f32_e32 v29, 1.0, v29
	v_rcp_f32_e32 v27, v27
	v_fmac_f32_e32 v6, v19, v26
	v_add_f32_e32 v31, 1.0, v31
	v_rcp_f32_e32 v29, v29
	v_fmac_f32_e32 v6, v20, v28
	v_rcp_f32_e32 v31, v31
	v_fmac_f32_e32 v6, v21, v30
	v_fmac_f32_e32 v6, v22, v7
	v_fmac_f32_e32 v6, v23, v27
	v_fmac_f32_e32 v6, v24, v29
	v_fmac_f32_e32 v6, v25, v31
	s_nop 1
	v_add_f32_dpp v6, v6, v6 row_shr:1 row_mask:0xf bank_mask:0xf bound_ctrl:0
	s_nop 1
	v_add_f32_dpp v6, v6, v6 row_shr:2 row_mask:0xf bank_mask:0xf bound_ctrl:0
	s_nop 1
	v_add_f32_dpp v6, v6, v6 row_shr:4 row_mask:0xf bank_mask:0xf bound_ctrl:0
	s_nop 1
	v_add_f32_dpp v6, v6, v6 row_shr:8 row_mask:0xf bank_mask:0xf bound_ctrl:0
	s_nop 1
	v_add_f32_dpp v6, v6, v6 row_bcast:15 row_mask:0xa bank_mask:0xf
	s_nop 1
	v_add_f32_dpp v6, v6, v6 row_bcast:31 row_mask:0xc bank_mask:0xf
	s_nop 1
	v_readlane_b32 s10, v6, 63
	s_nop 1
	v_mov_b32_e32 v6, s10
	v_mul_f32_e32 v6, 0x3b000000, v6
	v_fma_f32 v19, v19, v26, -v6
	v_fma_f32 v18, v18, v32, -v6
	v_mul_f32_e32 v19, v19, v19
	v_fma_f32 v20, v20, v28, -v6
	v_fmac_f32_e32 v19, v18, v18
	v_fma_f32 v21, v21, v30, -v6
	v_fmac_f32_e32 v19, v20, v20
	v_fma_f32 v7, v22, v7, -v6
	v_fmac_f32_e32 v19, v21, v21
	v_fma_f32 v22, v23, v27, -v6
	v_fmac_f32_e32 v19, v7, v7
	v_fma_f32 v23, v24, v29, -v6
	v_fmac_f32_e32 v19, v22, v22
	v_fmac_f32_e32 v19, v23, v23
	v_fma_f32 v7, v25, v31, -v6
	v_fmac_f32_e32 v19, v7, v7
	v_mov_b32_e32 v7, v19
	s_nop 1
	v_add_f32_dpp v7, v7, v7 row_shr:1 row_mask:0xf bank_mask:0xf bound_ctrl:0
	s_nop 1
	v_add_f32_dpp v7, v7, v7 row_shr:2 row_mask:0xf bank_mask:0xf bound_ctrl:0
	s_nop 1
	v_add_f32_dpp v7, v7, v7 row_shr:4 row_mask:0xf bank_mask:0xf bound_ctrl:0
	s_nop 1
	v_add_f32_dpp v7, v7, v7 row_shr:8 row_mask:0xf bank_mask:0xf bound_ctrl:0
	s_nop 1
	v_add_f32_dpp v7, v7, v7 row_bcast:15 row_mask:0xa bank_mask:0xf
	s_nop 1
	v_add_f32_dpp v7, v7, v7 row_bcast:31 row_mask:0xc bank_mask:0xf
	s_nop 1
	v_readlane_b32 s10, v7, 63
	s_nop 1
	v_mov_b32_e32 v7, s10
	v_mov_b32_e32 v18, 0
	s_and_saveexec_b64 s[56:57], s[42:43]
	s_cbranch_execz .LBB0_756
	s_waitcnt lgkmcnt(0)
	v_add_f32_e32 v7, v7, v18
	v_fmamk_f32 v7, v7, 0x3b000000, v194
	v_mul_f32_e32 v18, 0x4b800000, v7
	v_cmp_gt_f32_e32 vcc, s95, v7
	s_nop 1
	v_cndmask_b32_e32 v7, v7, v18, vcc
	v_rsq_f32_e32 v7, v7
	s_nop 0
	v_mul_f32_e32 v18, 0x45800000, v7
	v_cndmask_b32_e32 v7, v7, v18, vcc
	ds_write_b64 v17, v[6:7] offset:8
; DI float gelu_t(float x) { return x * sigm(1.5957691216057308f * (x + 0.044715f * x * x * x)); }
; DI void prep_a_prompt(LAS unsigned char* lds, const Params& P, int l, int unit) {
;     ...
;     for (int i = 0; i < 16; ++i) { const int t = wave * 16 + i; const float* p = P32 + (size_t)(row0 + t) * LDP + C_AV + lane * 8;
;         const f32x4 a = *(const f32x4*)p, bq = *(const f32x4*)(p + 4); float x[8];
; #pragma unroll
;         for (int e = 0; e < 4; ++e) { x[e] = gelu_t(a[e]); x[4 + e] = gelu_t(bq[e]); }
;         float s = 0.f;
; #pragma unroll
;         for (int e = 0; e < 8; ++e) s += x[e];
;         const float mean = wsum(s) * (1.f / 512.f); float d = 0.f;
; #pragma unroll
;         for (int e = 0; e < 8; ++e) d += (x[e] - mean) * (x[e] - mean);
;         const float var = wsum(d) * (1.f / 512.f);
;         if (lane == 0) { st[t * 2] = mean; st[t * 2 + 1] = rsqrtf(var + 1e-6f); } }
.LBB0_756:
	s_or_b64 exec, exec, s[56:57]
	s_waitcnt lgkmcnt(0)
	v_add_co_u32_e32 v18, vcc, 0xd000, v4
	s_mov_b64 s[6:7], 0xd800
	s_nop 0
	v_addc_co_u32_e32 v19, vcc, 0, v5, vcc
	v_lshl_add_u64 v[6:7], v[4:5], 0, s[6:7]
	s_nop 0
	s_waitcnt vmcnt(11)
	v_mov_b32_e32 v18, v72
	v_mov_b32_e32 v19, v73
	v_mov_b32_e32 v20, v74
	v_mov_b32_e32 v21, v75
	v_mul_f32_e32 v6, 0x3d372713, v18
	v_mul_f32_e32 v26, 0x3d372713, v19
	v_mul_f32_e32 v6, v18, v6
	v_mul_f32_e32 v28, 0x3d372713, v20
	v_mul_f32_e32 v26, v19, v26
	v_fma_f32 v6, v18, v6, v18
	v_mul_f32_e32 v30, 0x3d372713, v21
	v_mul_f32_e32 v28, v20, v28
	v_fma_f32 v26, v19, v26, v19
	v_mul_f32_e32 v6, 0x3fcc422a, v6
	s_waitcnt vmcnt(10)
	v_mov_b32_e32 v22, v76
	v_mov_b32_e32 v23, v77
	v_mov_b32_e32 v24, v78
	v_mov_b32_e32 v25, v79
	v_mul_f32_e32 v7, 0x3d372713, v22
	v_mul_f32_e32 v30, v21, v30
	v_fma_f32 v28, v20, v28, v20
	v_mul_f32_e32 v26, 0x3fcc422a, v26
	v_mul_f32_e32 v6, 0xbfb8aa3b, v6
	v_mul_f32_e32 v27, 0x3d372713, v23
	v_mul_f32_e32 v7, v22, v7
	v_fma_f32 v30, v21, v30, v21
	v_mul_f32_e32 v28, 0x3fcc422a, v28
	v_mul_f32_e32 v26, 0xbfb8aa3b, v26
	v_exp_f32_e32 v6, v6
	v_mul_f32_e32 v29, 0x3d372713, v24
	v_mul_f32_e32 v27, v23, v27
	v_fma_f32 v7, v22, v7, v22
	v_mul_f32_e32 v30, 0x3fcc422a, v30
	v_mul_f32_e32 v28, 0xbfb8aa3b, v28
	v_exp_f32_e32 v26, v26
	v_mul_f32_e32 v31, 0x3d372713, v25
	v_mul_f32_e32 v29, v24, v29
	v_fma_f32 v27, v23, v27, v23
	v_mul_f32_e32 v7, 0x3fcc422a, v7
	v_mul_f32_e32 v30, 0xbfb8aa3b, v30
	v_exp_f32_e32 v28, v28
	v_mul_f32_e32 v31, v25, v31
	v_fma_f32 v29, v24, v29, v24
	v_mul_f32_e32 v27, 0x3fcc422a, v27
	v_mul_f32_e32 v7, 0xbfb8aa3b, v7
	v_exp_f32_e32 v30, v30
	v_fma_f32 v31, v25, v31, v25
	v_mul_f32_e32 v29, 0x3fcc422a, v29
	v_mul_f32_e32 v27, 0xbfb8aa3b, v27
	v_exp_f32_e32 v7, v7
	v_add_f32_e32 v6, 1.0, v6
	v_mul_f32_e32 v31, 0x3fcc422a, v31
	v_mul_f32_e32 v29, 0xbfb8aa3b, v29
	v_exp_f32_e32 v27, v27
	v_add_f32_e32 v26, 1.0, v26
	v_rcp_f32_e32 v32, v6
	v_mul_f32_e32 v31, 0xbfb8aa3b, v31
	v_exp_f32_e32 v29, v29
	v_add_f32_e32 v28, 1.0, v28
	v_rcp_f32_e32 v26, v26
	v_exp_f32_e32 v31, v31
	v_add_f32_e32 v30, 1.0, v30
	v_rcp_f32_e32 v28, v28
	v_add_f32_e32 v7, 1.0, v7
	v_rcp_f32_e32 v30, v30
	v_add_f32_e32 v27, 1.0, v27
	v_rcp_f32_e32 v7, v7
	v_fma_f32 v6, v18, v32, 0
	v_add_f32_e32 v29, 1.0, v29
	v_rcp_f32_e32 v27, v27
	v_fmac_f32_e32 v6, v19, v26
	v_add_f32_e32 v31, 1.0, v31
	v_rcp_f32_e32 v29, v29
	v_fmac_f32_e32 v6, v20, v28
	v_rcp_f32_e32 v31, v31
	v_fmac_f32_e32 v6, v21, v30
	v_fmac_f32_e32 v6, v22, v7
	v_fmac_f32_e32 v6, v23, v27
	v_fmac_f32_e32 v6, v24, v29
	v_fmac_f32_e32 v6, v25, v31
	s_nop 1
	v_add_f32_dpp v6, v6, v6 row_shr:1 row_mask:0xf bank_mask:0xf bound_ctrl:0
	s_nop 1
	v_add_f32_dpp v6, v6, v6 row_shr:2 row_mask:0xf bank_mask:0xf bound_ctrl:0
	s_nop 1
	v_add_f32_dpp v6, v6, v6 row_shr:4 row_mask:0xf bank_mask:0xf bound_ctrl:0
	s_nop 1
	v_add_f32_dpp v6, v6, v6 row_shr:8 row_mask:0xf bank_mask:0xf bound_ctrl:0
	s_nop 1
	v_add_f32_dpp v6, v6, v6 row_bcast:15 row_mask:0xa bank_mask:0xf
	s_nop 1
	v_add_f32_dpp v6, v6, v6 row_bcast:31 row_mask:0xc bank_mask:0xf
	s_nop 1
	v_readlane_b32 s10, v6, 63
	s_nop 1
	v_mov_b32_e32 v6, s10
	v_mul_f32_e32 v6, 0x3b000000, v6
	v_fma_f32 v19, v19, v26, -v6
	v_fma_f32 v18, v18, v32, -v6
	v_mul_f32_e32 v19, v19, v19
	v_fma_f32 v20, v20, v28, -v6
	v_fmac_f32_e32 v19, v18, v18
	v_fma_f32 v21, v21, v30, -v6
	v_fmac_f32_e32 v19, v20, v20
	v_fma_f32 v7, v22, v7, -v6
	v_fmac_f32_e32 v19, v21, v21
	v_fma_f32 v22, v23, v27, -v6
	v_fmac_f32_e32 v19, v7, v7
	v_fma_f32 v23, v24, v29, -v6
	v_fmac_f32_e32 v19, v22, v22
	v_fmac_f32_e32 v19, v23, v23
	v_fma_f32 v7, v25, v31, -v6
	v_fmac_f32_e32 v19, v7, v7
	v_mov_b32_e32 v7, v19
	s_nop 1
	v_add_f32_dpp v7, v7, v7 row_shr:1 row_mask:0xf bank_mask:0xf bound_ctrl:0
	s_nop 1
	v_add_f32_dpp v7, v7, v7 row_shr:2 row_mask:0xf bank_mask:0xf bound_ctrl:0
	s_nop 1
	v_add_f32_dpp v7, v7, v7 row_shr:4 row_mask:0xf bank_mask:0xf bound_ctrl:0
	s_nop 1
	v_add_f32_dpp v7, v7, v7 row_shr:8 row_mask:0xf bank_mask:0xf bound_ctrl:0
	s_nop 1
	v_add_f32_dpp v7, v7, v7 row_bcast:15 row_mask:0xa bank_mask:0xf
	s_nop 1
	v_add_f32_dpp v7, v7, v7 row_bcast:31 row_mask:0xc bank_mask:0xf
	s_nop 1
	v_readlane_b32 s10, v7, 63
	s_nop 1
	v_mov_b32_e32 v7, s10
	v_mov_b32_e32 v18, 0
	s_and_saveexec_b64 s[56:57], s[42:43]
	s_cbranch_execz .LBB0_758
	s_waitcnt lgkmcnt(0)
	v_add_f32_e32 v7, v7, v18
	v_fmamk_f32 v7, v7, 0x3b000000, v194
	v_mul_f32_e32 v18, 0x4b800000, v7
	v_cmp_gt_f32_e32 vcc, s95, v7
	s_nop 1
	v_cndmask_b32_e32 v7, v7, v18, vcc
	v_rsq_f32_e32 v7, v7
	s_nop 0
	v_mul_f32_e32 v18, 0x45800000, v7
	v_cndmask_b32_e32 v7, v7, v18, vcc
	ds_write_b64 v17, v[6:7] offset:16
; DI float gelu_t(float x) { return x * sigm(1.5957691216057308f * (x + 0.044715f * x * x * x)); }
; DI void prep_a_prompt(LAS unsigned char* lds, const Params& P, int l, int unit) {
;     ...
;     for (int i = 0; i < 16; ++i) { const int t = wave * 16 + i; const float* p = P32 + (size_t)(row0 + t) * LDP + C_AV + lane * 8;
;         const f32x4 a = *(const f32x4*)p, bq = *(const f32x4*)(p + 4); float x[8];
; #pragma unroll
;         for (int e = 0; e < 4; ++e) { x[e] = gelu_t(a[e]); x[4 + e] = gelu_t(bq[e]); }
;         float s = 0.f;
; #pragma unroll
;         for (int e = 0; e < 8; ++e) s += x[e];
;         const float mean = wsum(s) * (1.f / 512.f); float d = 0.f;
; #pragma unroll
;         for (int e = 0; e < 8; ++e) d += (x[e] - mean) * (x[e] - mean);
;         const float var = wsum(d) * (1.f / 512.f);
;         if (lane == 0) { st[t * 2] = mean; st[t * 2 + 1] = rsqrtf(var + 1e-6f); } }
.LBB0_758:
	s_or_b64 exec, exec, s[56:57]
	s_waitcnt lgkmcnt(0)
	v_add_co_u32_e32 v18, vcc, 0x14000, v4
	s_mov_b64 s[6:7], 0x14000
	s_nop 0
	v_addc_co_u32_e32 v19, vcc, 0, v5, vcc
	v_lshl_add_u64 v[6:7], v[4:5], 0, s[6:7]
	s_nop 0
	s_waitcnt vmcnt(9)
	v_mov_b32_e32 v18, v80
	v_mov_b32_e32 v19, v81
	v_mov_b32_e32 v20, v82
	v_mov_b32_e32 v21, v83
	v_mul_f32_e32 v6, 0x3d372713, v18
	v_mul_f32_e32 v26, 0x3d372713, v19
	v_mul_f32_e32 v6, v18, v6
	v_mul_f32_e32 v28, 0x3d372713, v20
	v_mul_f32_e32 v26, v19, v26
	v_fma_f32 v6, v18, v6, v18
	v_mul_f32_e32 v30, 0x3d372713, v21
	v_mul_f32_e32 v28, v20, v28
	v_fma_f32 v26, v19, v26, v19
	v_mul_f32_e32 v6, 0x3fcc422a, v6
	s_waitcnt vmcnt(8)
	v_mov_b32_e32 v22, v84
	v_mov_b32_e32 v23, v85
	v_mov_b32_e32 v24, v86
	v_mov_b32_e32 v25, v87
	v_mul_f32_e32 v7, 0x3d372713, v22
	v_mul_f32_e32 v30, v21, v30
	v_fma_f32 v28, v20, v28, v20
	v_mul_f32_e32 v26, 0x3fcc422a, v26
	v_mul_f32_e32 v6, 0xbfb8aa3b, v6
	v_mul_f32_e32 v27, 0x3d372713, v23
	v_mul_f32_e32 v7, v22, v7
	v_fma_f32 v30, v21, v30, v21
	v_mul_f32_e32 v28, 0x3fcc422a, v28
	v_mul_f32_e32 v26, 0xbfb8aa3b, v26
	v_exp_f32_e32 v6, v6
	v_mul_f32_e32 v29, 0x3d372713, v24
	v_mul_f32_e32 v27, v23, v27
	v_fma_f32 v7, v22, v7, v22
	v_mul_f32_e32 v30, 0x3fcc422a, v30
	v_mul_f32_e32 v28, 0xbfb8aa3b, v28
	v_exp_f32_e32 v26, v26
	v_mul_f32_e32 v31, 0x3d372713, v25
	v_mul_f32_e32 v29, v24, v29
	v_fma_f32 v27, v23, v27, v23
	v_mul_f32_e32 v7, 0x3fcc422a, v7
	v_mul_f32_e32 v30, 0xbfb8aa3b, v30
	v_exp_f32_e32 v28, v28
	v_mul_f32_e32 v31, v25, v31
	v_fma_f32 v29, v24, v29, v24
	v_mul_f32_e32 v27, 0x3fcc422a, v27
	v_mul_f32_e32 v7, 0xbfb8aa3b, v7
	v_exp_f32_e32 v30, v30
	v_fma_f32 v31, v25, v31, v25
	v_mul_f32_e32 v29, 0x3fcc422a, v29
	v_mul_f32_e32 v27, 0xbfb8aa3b, v27
	v_exp_f32_e32 v7, v7
	v_add_f32_e32 v6, 1.0, v6
	v_mul_f32_e32 v31, 0x3fcc422a, v31
	v_mul_f32_e32 v29, 0xbfb8aa3b, v29
	v_exp_f32_e32 v27, v27
	v_add_f32_e32 v26, 1.0, v26
	v_rcp_f32_e32 v32, v6
	v_mul_f32_e32 v31, 0xbfb8aa3b, v31
	v_exp_f32_e32 v29, v29
	v_add_f32_e32 v28, 1.0, v28
	v_rcp_f32_e32 v26, v26
	v_exp_f32_e32 v31, v31
	v_add_f32_e32 v30, 1.0, v30
	v_rcp_f32_e32 v28, v28
	v_add_f32_e32 v7, 1.0, v7
	v_rcp_f32_e32 v30, v30
	v_add_f32_e32 v27, 1.0, v27
	v_rcp_f32_e32 v7, v7
	v_fma_f32 v6, v18, v32, 0
	v_add_f32_e32 v29, 1.0, v29
	v_rcp_f32_e32 v27, v27
	v_fmac_f32_e32 v6, v19, v26
	v_add_f32_e32 v31, 1.0, v31
	v_rcp_f32_e32 v29, v29
	v_fmac_f32_e32 v6, v20, v28
	v_rcp_f32_e32 v31, v31
	v_fmac_f32_e32 v6, v21, v30
	v_fmac_f32_e32 v6, v22, v7
	v_fmac_f32_e32 v6, v23, v27
	v_fmac_f32_e32 v6, v24, v29
	v_fmac_f32_e32 v6, v25, v31
	s_nop 1
	v_add_f32_dpp v6, v6, v6 row_shr:1 row_mask:0xf bank_mask:0xf bound_ctrl:0
	s_nop 1
	v_add_f32_dpp v6, v6, v6 row_shr:2 row_mask:0xf bank_mask:0xf bound_ctrl:0
	s_nop 1
	v_add_f32_dpp v6, v6, v6 row_shr:4 row_mask:0xf bank_mask:0xf bound_ctrl:0
	s_nop 1
	v_add_f32_dpp v6, v6, v6 row_shr:8 row_mask:0xf bank_mask:0xf bound_ctrl:0
	s_nop 1
	v_add_f32_dpp v6, v6, v6 row_bcast:15 row_mask:0xa bank_mask:0xf
	s_nop 1
	v_add_f32_dpp v6, v6, v6 row_bcast:31 row_mask:0xc bank_mask:0xf
	s_nop 1
	v_readlane_b32 s10, v6, 63
	s_nop 1
	v_mov_b32_e32 v6, s10
	v_mul_f32_e32 v6, 0x3b000000, v6
	v_fma_f32 v19, v19, v26, -v6
	v_fma_f32 v18, v18, v32, -v6
	v_mul_f32_e32 v19, v19, v19
	v_fma_f32 v20, v20, v28, -v6
	v_fmac_f32_e32 v19, v18, v18
	v_fma_f32 v21, v21, v30, -v6
	v_fmac_f32_e32 v19, v20, v20
	v_fma_f32 v7, v22, v7, -v6
	v_fmac_f32_e32 v19, v21, v21
	v_fma_f32 v22, v23, v27, -v6
	v_fmac_f32_e32 v19, v7, v7
	v_fma_f32 v23, v24, v29, -v6
	v_fmac_f32_e32 v19, v22, v22
	v_fmac_f32_e32 v19, v23, v23
	v_fma_f32 v7, v25, v31, -v6
	v_fmac_f32_e32 v19, v7, v7
	v_mov_b32_e32 v7, v19
	s_nop 1
	v_add_f32_dpp v7, v7, v7 row_shr:1 row_mask:0xf bank_mask:0xf bound_ctrl:0
	s_nop 1
	v_add_f32_dpp v7, v7, v7 row_shr:2 row_mask:0xf bank_mask:0xf bound_ctrl:0
	s_nop 1
	v_add_f32_dpp v7, v7, v7 row_shr:4 row_mask:0xf bank_mask:0xf bound_ctrl:0
	s_nop 1
	v_add_f32_dpp v7, v7, v7 row_shr:8 row_mask:0xf bank_mask:0xf bound_ctrl:0
	s_nop 1
	v_add_f32_dpp v7, v7, v7 row_bcast:15 row_mask:0xa bank_mask:0xf
	s_nop 1
	v_add_f32_dpp v7, v7, v7 row_bcast:31 row_mask:0xc bank_mask:0xf
	s_nop 1
	v_readlane_b32 s10, v7, 63
	s_nop 1
	v_mov_b32_e32 v7, s10
	v_mov_b32_e32 v18, 0
	s_and_saveexec_b64 s[56:57], s[42:43]
	s_cbranch_execz .LBB0_760
	s_waitcnt lgkmcnt(0)
	v_add_f32_e32 v7, v7, v18
	v_fmamk_f32 v7, v7, 0x3b000000, v194
	v_mul_f32_e32 v18, 0x4b800000, v7
	v_cmp_gt_f32_e32 vcc, s95, v7
	s_nop 1
	v_cndmask_b32_e32 v7, v7, v18, vcc
	v_rsq_f32_e32 v7, v7
	s_nop 0
	v_mul_f32_e32 v18, 0x45800000, v7
	v_cndmask_b32_e32 v7, v7, v18, vcc
	ds_write_b64 v17, v[6:7] offset:24
; DI float gelu_t(float x) { return x * sigm(1.5957691216057308f * (x + 0.044715f * x * x * x)); }
; DI void prep_a_prompt(LAS unsigned char* lds, const Params& P, int l, int unit) {
;     ...
;     for (int i = 0; i < 16; ++i) { const int t = wave * 16 + i; const float* p = P32 + (size_t)(row0 + t) * LDP + C_AV + lane * 8;
;         const f32x4 a = *(const f32x4*)p, bq = *(const f32x4*)(p + 4); float x[8];
; #pragma unroll
;         for (int e = 0; e < 4; ++e) { x[e] = gelu_t(a[e]); x[4 + e] = gelu_t(bq[e]); }
;         float s = 0.f;
; #pragma unroll
;         for (int e = 0; e < 8; ++e) s += x[e];
;         const float mean = wsum(s) * (1.f / 512.f); float d = 0.f;
; #pragma unroll
;         for (int e = 0; e < 8; ++e) d += (x[e] - mean) * (x[e] - mean);
;         const float var = wsum(d) * (1.f / 512.f);
;         if (lane == 0) { st[t * 2] = mean; st[t * 2 + 1] = rsqrtf(var + 1e-6f); } }
.LBB0_760:
	s_or_b64 exec, exec, s[56:57]
	s_waitcnt lgkmcnt(0)
	v_add_co_u32_e32 v18, vcc, 0x1a000, v4
	s_mov_b64 s[6:7], 0x1a800
	s_nop 0
	v_addc_co_u32_e32 v19, vcc, 0, v5, vcc
	v_lshl_add_u64 v[6:7], v[4:5], 0, s[6:7]
	s_nop 0
	s_waitcnt vmcnt(7)
	v_mov_b32_e32 v18, v88
	v_mov_b32_e32 v19, v89
	v_mov_b32_e32 v20, v90
	v_mov_b32_e32 v21, v91
	v_mul_f32_e32 v6, 0x3d372713, v18
	v_mul_f32_e32 v26, 0x3d372713, v19
	v_mul_f32_e32 v6, v18, v6
	v_mul_f32_e32 v28, 0x3d372713, v20
	v_mul_f32_e32 v26, v19, v26
	v_fma_f32 v6, v18, v6, v18
	v_mul_f32_e32 v30, 0x3d372713, v21
	v_mul_f32_e32 v28, v20, v28
	v_fma_f32 v26, v19, v26, v19
	v_mul_f32_e32 v6, 0x3fcc422a, v6
	s_waitcnt vmcnt(6)
	v_mov_b32_e32 v22, v92
	v_mov_b32_e32 v23, v93
	v_mov_b32_e32 v24, v94
	v_mov_b32_e32 v25, v95
	v_mul_f32_e32 v7, 0x3d372713, v22
	v_mul_f32_e32 v30, v21, v30
	v_fma_f32 v28, v20, v28, v20
	v_mul_f32_e32 v26, 0x3fcc422a, v26
	v_mul_f32_e32 v6, 0xbfb8aa3b, v6
	v_mul_f32_e32 v27, 0x3d372713, v23
	v_mul_f32_e32 v7, v22, v7
	v_fma_f32 v30, v21, v30, v21
	v_mul_f32_e32 v28, 0x3fcc422a, v28
	v_mul_f32_e32 v26, 0xbfb8aa3b, v26
	v_exp_f32_e32 v6, v6
	v_mul_f32_e32 v29, 0x3d372713, v24
	v_mul_f32_e32 v27, v23, v27
	v_fma_f32 v7, v22, v7, v22
	v_mul_f32_e32 v30, 0x3fcc422a, v30
	v_mul_f32_e32 v28, 0xbfb8aa3b, v28
	v_exp_f32_e32 v26, v26
	v_mul_f32_e32 v31, 0x3d372713, v25
	v_mul_f32_e32 v29, v24, v29
	v_fma_f32 v27, v23, v27, v23
	v_mul_f32_e32 v7, 0x3fcc422a, v7
	v_mul_f32_e32 v30, 0xbfb8aa3b, v30
	v_exp_f32_e32 v28, v28
	v_mul_f32_e32 v31, v25, v31
	v_fma_f32 v29, v24, v29, v24
	v_mul_f32_e32 v27, 0x3fcc422a, v27
	v_mul_f32_e32 v7, 0xbfb8aa3b, v7
	v_exp_f32_e32 v30, v30
	v_fma_f32 v31, v25, v31, v25
	v_mul_f32_e32 v29, 0x3fcc422a, v29
	v_mul_f32_e32 v27, 0xbfb8aa3b, v27
	v_exp_f32_e32 v7, v7
	v_add_f32_e32 v6, 1.0, v6
	v_mul_f32_e32 v31, 0x3fcc422a, v31
	v_mul_f32_e32 v29, 0xbfb8aa3b, v29
	v_exp_f32_e32 v27, v27
	v_add_f32_e32 v26, 1.0, v26
	v_rcp_f32_e32 v32, v6
	v_mul_f32_e32 v31, 0xbfb8aa3b, v31
	v_exp_f32_e32 v29, v29
	v_add_f32_e32 v28, 1.0, v28
	v_rcp_f32_e32 v26, v26
	v_exp_f32_e32 v31, v31
	v_add_f32_e32 v30, 1.0, v30
	v_rcp_f32_e32 v28, v28
	v_add_f32_e32 v7, 1.0, v7
	v_rcp_f32_e32 v30, v30
	v_add_f32_e32 v27, 1.0, v27
	v_rcp_f32_e32 v7, v7
	v_fma_f32 v6, v18, v32, 0
	v_add_f32_e32 v29, 1.0, v29
	v_rcp_f32_e32 v27, v27
	v_fmac_f32_e32 v6, v19, v26
	v_add_f32_e32 v31, 1.0, v31
	v_rcp_f32_e32 v29, v29
	v_fmac_f32_e32 v6, v20, v28
	v_rcp_f32_e32 v31, v31
	v_fmac_f32_e32 v6, v21, v30
	v_fmac_f32_e32 v6, v22, v7
	v_fmac_f32_e32 v6, v23, v27
	v_fmac_f32_e32 v6, v24, v29
	v_fmac_f32_e32 v6, v25, v31
	s_nop 1
	v_add_f32_dpp v6, v6, v6 row_shr:1 row_mask:0xf bank_mask:0xf bound_ctrl:0
	s_nop 1
	v_add_f32_dpp v6, v6, v6 row_shr:2 row_mask:0xf bank_mask:0xf bound_ctrl:0
	s_nop 1
	v_add_f32_dpp v6, v6, v6 row_shr:4 row_mask:0xf bank_mask:0xf bound_ctrl:0
	s_nop 1
	v_add_f32_dpp v6, v6, v6 row_shr:8 row_mask:0xf bank_mask:0xf bound_ctrl:0
	s_nop 1
	v_add_f32_dpp v6, v6, v6 row_bcast:15 row_mask:0xa bank_mask:0xf
	s_nop 1
	v_add_f32_dpp v6, v6, v6 row_bcast:31 row_mask:0xc bank_mask:0xf
	s_nop 1
	v_readlane_b32 s10, v6, 63
	s_nop 1
	v_mov_b32_e32 v6, s10
	v_mul_f32_e32 v6, 0x3b000000, v6
	v_fma_f32 v19, v19, v26, -v6
	v_fma_f32 v18, v18, v32, -v6
	v_mul_f32_e32 v19, v19, v19
	v_fma_f32 v20, v20, v28, -v6
	v_fmac_f32_e32 v19, v18, v18
	v_fma_f32 v21, v21, v30, -v6
	v_fmac_f32_e32 v19, v20, v20
	v_fma_f32 v7, v22, v7, -v6
	v_fmac_f32_e32 v19, v21, v21
	v_fma_f32 v22, v23, v27, -v6
	v_fmac_f32_e32 v19, v7, v7
	v_fma_f32 v23, v24, v29, -v6
	v_fmac_f32_e32 v19, v22, v22
	v_fmac_f32_e32 v19, v23, v23
	v_fma_f32 v7, v25, v31, -v6
	v_fmac_f32_e32 v19, v7, v7
	v_mov_b32_e32 v7, v19
	s_nop 1
	v_add_f32_dpp v7, v7, v7 row_shr:1 row_mask:0xf bank_mask:0xf bound_ctrl:0
	s_nop 1
	v_add_f32_dpp v7, v7, v7 row_shr:2 row_mask:0xf bank_mask:0xf bound_ctrl:0
	s_nop 1
	v_add_f32_dpp v7, v7, v7 row_shr:4 row_mask:0xf bank_mask:0xf bound_ctrl:0
	s_nop 1
	v_add_f32_dpp v7, v7, v7 row_shr:8 row_mask:0xf bank_mask:0xf bound_ctrl:0
	s_nop 1
	v_add_f32_dpp v7, v7, v7 row_bcast:15 row_mask:0xa bank_mask:0xf
	s_nop 1
	v_add_f32_dpp v7, v7, v7 row_bcast:31 row_mask:0xc bank_mask:0xf
	s_nop 1
	v_readlane_b32 s10, v7, 63
	s_nop 1
	v_mov_b32_e32 v7, s10
	v_mov_b32_e32 v18, 0
	s_and_saveexec_b64 s[56:57], s[42:43]
	s_cbranch_execz .LBB0_762
	s_waitcnt lgkmcnt(0)
	v_add_f32_e32 v7, v7, v18
	v_fmamk_f32 v7, v7, 0x3b000000, v194
	v_mul_f32_e32 v18, 0x4b800000, v7
	v_cmp_gt_f32_e32 vcc, s95, v7
	s_nop 1
	v_cndmask_b32_e32 v7, v7, v18, vcc
	v_rsq_f32_e32 v7, v7
	s_nop 0
	v_mul_f32_e32 v18, 0x45800000, v7
	v_cndmask_b32_e32 v7, v7, v18, vcc
	ds_write_b64 v17, v[6:7] offset:32
; DI float gelu_t(float x) { return x * sigm(1.5957691216057308f * (x + 0.044715f * x * x * x)); }
; DI void prep_a_prompt(LAS unsigned char* lds, const Params& P, int l, int unit) {
;     ...
;     for (int i = 0; i < 16; ++i) { const int t = wave * 16 + i; const float* p = P32 + (size_t)(row0 + t) * LDP + C_AV + lane * 8;
;         const f32x4 a = *(const f32x4*)p, bq = *(const f32x4*)(p + 4); float x[8];
; #pragma unroll
;         for (int e = 0; e < 4; ++e) { x[e] = gelu_t(a[e]); x[4 + e] = gelu_t(bq[e]); }
;         float s = 0.f;
; #pragma unroll
;         for (int e = 0; e < 8; ++e) s += x[e];
;         const float mean = wsum(s) * (1.f / 512.f); float d = 0.f;
; #pragma unroll
;         for (int e = 0; e < 8; ++e) d += (x[e] - mean) * (x[e] - mean);
;         const float var = wsum(d) * (1.f / 512.f);
;         if (lane == 0) { st[t * 2] = mean; st[t * 2 + 1] = rsqrtf(var + 1e-6f); } }
.LBB0_762:
	s_or_b64 exec, exec, s[56:57]
	s_waitcnt lgkmcnt(0)
	v_add_co_u32_e32 v18, vcc, 0x21000, v4
	s_mov_b64 s[6:7], 0x21000
	s_nop 0
	v_addc_co_u32_e32 v19, vcc, 0, v5, vcc
	v_lshl_add_u64 v[6:7], v[4:5], 0, s[6:7]
	s_nop 0
	s_waitcnt vmcnt(5)
	v_mov_b32_e32 v18, v96
	v_mov_b32_e32 v19, v97
	v_mov_b32_e32 v20, v98
	v_mov_b32_e32 v21, v99
	v_mul_f32_e32 v6, 0x3d372713, v18
	v_mul_f32_e32 v26, 0x3d372713, v19
	v_mul_f32_e32 v6, v18, v6
	v_mul_f32_e32 v28, 0x3d372713, v20
	v_mul_f32_e32 v26, v19, v26
	v_fma_f32 v6, v18, v6, v18
	v_mul_f32_e32 v30, 0x3d372713, v21
	v_mul_f32_e32 v28, v20, v28
	v_fma_f32 v26, v19, v26, v19
	v_mul_f32_e32 v6, 0x3fcc422a, v6
	s_waitcnt vmcnt(4)
	v_mov_b32_e32 v22, v100
	v_mov_b32_e32 v23, v101
	v_mov_b32_e32 v24, v102
	v_mov_b32_e32 v25, v103
	v_mul_f32_e32 v7, 0x3d372713, v22
	v_mul_f32_e32 v30, v21, v30
	v_fma_f32 v28, v20, v28, v20
	v_mul_f32_e32 v26, 0x3fcc422a, v26
	v_mul_f32_e32 v6, 0xbfb8aa3b, v6
	v_mul_f32_e32 v27, 0x3d372713, v23
	v_mul_f32_e32 v7, v22, v7
	v_fma_f32 v30, v21, v30, v21
	v_mul_f32_e32 v28, 0x3fcc422a, v28
	v_mul_f32_e32 v26, 0xbfb8aa3b, v26
	v_exp_f32_e32 v6, v6
	v_mul_f32_e32 v29, 0x3d372713, v24
	v_mul_f32_e32 v27, v23, v27
	v_fma_f32 v7, v22, v7, v22
	v_mul_f32_e32 v30, 0x3fcc422a, v30
	v_mul_f32_e32 v28, 0xbfb8aa3b, v28
	v_exp_f32_e32 v26, v26
	v_mul_f32_e32 v31, 0x3d372713, v25
	v_mul_f32_e32 v29, v24, v29
	v_fma_f32 v27, v23, v27, v23
	v_mul_f32_e32 v7, 0x3fcc422a, v7
	v_mul_f32_e32 v30, 0xbfb8aa3b, v30
	v_exp_f32_e32 v28, v28
	v_mul_f32_e32 v31, v25, v31
	v_fma_f32 v29, v24, v29, v24
	v_mul_f32_e32 v27, 0x3fcc422a, v27
	v_mul_f32_e32 v7, 0xbfb8aa3b, v7
	v_exp_f32_e32 v30, v30
	v_fma_f32 v31, v25, v31, v25
	v_mul_f32_e32 v29, 0x3fcc422a, v29
	v_mul_f32_e32 v27, 0xbfb8aa3b, v27
	v_exp_f32_e32 v7, v7
	v_add_f32_e32 v6, 1.0, v6
	v_mul_f32_e32 v31, 0x3fcc422a, v31
	v_mul_f32_e32 v29, 0xbfb8aa3b, v29
	v_exp_f32_e32 v27, v27
	v_add_f32_e32 v26, 1.0, v26
	v_rcp_f32_e32 v32, v6
	v_mul_f32_e32 v31, 0xbfb8aa3b, v31
	v_exp_f32_e32 v29, v29
	v_add_f32_e32 v28, 1.0, v28
	v_rcp_f32_e32 v26, v26
	v_exp_f32_e32 v31, v31
	v_add_f32_e32 v30, 1.0, v30
	v_rcp_f32_e32 v28, v28
	v_add_f32_e32 v7, 1.0, v7
	v_rcp_f32_e32 v30, v30
	v_add_f32_e32 v27, 1.0, v27
	v_rcp_f32_e32 v7, v7
	v_fma_f32 v6, v18, v32, 0
	v_add_f32_e32 v29, 1.0, v29
	v_rcp_f32_e32 v27, v27
	v_fmac_f32_e32 v6, v19, v26
	v_add_f32_e32 v31, 1.0, v31
	v_rcp_f32_e32 v29, v29
	v_fmac_f32_e32 v6, v20, v28
	v_rcp_f32_e32 v31, v31
	v_fmac_f32_e32 v6, v21, v30
	v_fmac_f32_e32 v6, v22, v7
	v_fmac_f32_e32 v6, v23, v27
	v_fmac_f32_e32 v6, v24, v29
	v_fmac_f32_e32 v6, v25, v31
	s_nop 1
	v_add_f32_dpp v6, v6, v6 row_shr:1 row_mask:0xf bank_mask:0xf bound_ctrl:0
	s_nop 1
	v_add_f32_dpp v6, v6, v6 row_shr:2 row_mask:0xf bank_mask:0xf bound_ctrl:0
	s_nop 1
	v_add_f32_dpp v6, v6, v6 row_shr:4 row_mask:0xf bank_mask:0xf bound_ctrl:0
	s_nop 1
	v_add_f32_dpp v6, v6, v6 row_shr:8 row_mask:0xf bank_mask:0xf bound_ctrl:0
	s_nop 1
	v_add_f32_dpp v6, v6, v6 row_bcast:15 row_mask:0xa bank_mask:0xf
	s_nop 1
	v_add_f32_dpp v6, v6, v6 row_bcast:31 row_mask:0xc bank_mask:0xf
	s_nop 1
	v_readlane_b32 s10, v6, 63
	s_nop 1
	v_mov_b32_e32 v6, s10
	v_mul_f32_e32 v6, 0x3b000000, v6
	v_fma_f32 v19, v19, v26, -v6
	v_fma_f32 v18, v18, v32, -v6
	v_mul_f32_e32 v19, v19, v19
	v_fma_f32 v20, v20, v28, -v6
	v_fmac_f32_e32 v19, v18, v18
	v_fma_f32 v21, v21, v30, -v6
	v_fmac_f32_e32 v19, v20, v20
	v_fma_f32 v7, v22, v7, -v6
	v_fmac_f32_e32 v19, v21, v21
	v_fma_f32 v22, v23, v27, -v6
	v_fmac_f32_e32 v19, v7, v7
	v_fma_f32 v23, v24, v29, -v6
	v_fmac_f32_e32 v19, v22, v22
	v_fmac_f32_e32 v19, v23, v23
	v_fma_f32 v7, v25, v31, -v6
	v_fmac_f32_e32 v19, v7, v7
	v_mov_b32_e32 v7, v19
	s_nop 1
	v_add_f32_dpp v7, v7, v7 row_shr:1 row_mask:0xf bank_mask:0xf bound_ctrl:0
	s_nop 1
	v_add_f32_dpp v7, v7, v7 row_shr:2 row_mask:0xf bank_mask:0xf bound_ctrl:0
	s_nop 1
	v_add_f32_dpp v7, v7, v7 row_shr:4 row_mask:0xf bank_mask:0xf bound_ctrl:0
	s_nop 1
	v_add_f32_dpp v7, v7, v7 row_shr:8 row_mask:0xf bank_mask:0xf bound_ctrl:0
	s_nop 1
	v_add_f32_dpp v7, v7, v7 row_bcast:15 row_mask:0xa bank_mask:0xf
	s_nop 1
	v_add_f32_dpp v7, v7, v7 row_bcast:31 row_mask:0xc bank_mask:0xf
	s_nop 1
	v_readlane_b32 s10, v7, 63
	s_nop 1
	v_mov_b32_e32 v7, s10
	v_mov_b32_e32 v18, 0
	s_and_saveexec_b64 s[56:57], s[42:43]
	s_cbranch_execz .LBB0_764
	s_waitcnt lgkmcnt(0)
	v_add_f32_e32 v7, v7, v18
	v_fmamk_f32 v7, v7, 0x3b000000, v194
	v_mul_f32_e32 v18, 0x4b800000, v7
	v_cmp_gt_f32_e32 vcc, s95, v7
	s_nop 1
	v_cndmask_b32_e32 v7, v7, v18, vcc
	v_rsq_f32_e32 v7, v7
	s_nop 0
	v_mul_f32_e32 v18, 0x45800000, v7
	v_cndmask_b32_e32 v7, v7, v18, vcc
	ds_write_b64 v17, v[6:7] offset:40
; DI float gelu_t(float x) { return x * sigm(1.5957691216057308f * (x + 0.044715f * x * x * x)); }
; DI void prep_a_prompt(LAS unsigned char* lds, const Params& P, int l, int unit) {
;     ...
;     for (int i = 0; i < 16; ++i) { const int t = wave * 16 + i; const float* p = P32 + (size_t)(row0 + t) * LDP + C_AV + lane * 8;
;         const f32x4 a = *(const f32x4*)p, bq = *(const f32x4*)(p + 4); float x[8];
; #pragma unroll
;         for (int e = 0; e < 4; ++e) { x[e] = gelu_t(a[e]); x[4 + e] = gelu_t(bq[e]); }
;         float s = 0.f;
; #pragma unroll
;         for (int e = 0; e < 8; ++e) s += x[e];
;         const float mean = wsum(s) * (1.f / 512.f); float d = 0.f;
; #pragma unroll
;         for (int e = 0; e < 8; ++e) d += (x[e] - mean) * (x[e] - mean);
;         const float var = wsum(d) * (1.f / 512.f);
;         if (lane == 0) { st[t * 2] = mean; st[t * 2 + 1] = rsqrtf(var + 1e-6f); } }
.LBB0_764:
	s_or_b64 exec, exec, s[56:57]
	s_waitcnt lgkmcnt(0)
	v_add_co_u32_e32 v18, vcc, 0x27000, v4
	s_mov_b64 s[6:7], 0x27800
	s_nop 0
	v_addc_co_u32_e32 v19, vcc, 0, v5, vcc
	v_lshl_add_u64 v[6:7], v[4:5], 0, s[6:7]
	s_nop 0
	s_waitcnt vmcnt(3)
	v_mov_b32_e32 v18, v104
	v_mov_b32_e32 v19, v105
	v_mov_b32_e32 v20, v106
	v_mov_b32_e32 v21, v107
	v_mul_f32_e32 v6, 0x3d372713, v18
	v_mul_f32_e32 v26, 0x3d372713, v19
	v_mul_f32_e32 v6, v18, v6
	v_mul_f32_e32 v28, 0x3d372713, v20
	v_mul_f32_e32 v26, v19, v26
	v_fma_f32 v6, v18, v6, v18
	v_mul_f32_e32 v30, 0x3d372713, v21
	v_mul_f32_e32 v28, v20, v28
	v_fma_f32 v26, v19, v26, v19
	v_mul_f32_e32 v6, 0x3fcc422a, v6
	s_waitcnt vmcnt(2)
	v_mov_b32_e32 v22, v108
	v_mov_b32_e32 v23, v109
	v_mov_b32_e32 v24, v110
	v_mov_b32_e32 v25, v111
	v_mul_f32_e32 v7, 0x3d372713, v22
	v_mul_f32_e32 v30, v21, v30
	v_fma_f32 v28, v20, v28, v20
	v_mul_f32_e32 v26, 0x3fcc422a, v26
	v_mul_f32_e32 v6, 0xbfb8aa3b, v6
	v_mul_f32_e32 v27, 0x3d372713, v23
	v_mul_f32_e32 v7, v22, v7
	v_fma_f32 v30, v21, v30, v21
	v_mul_f32_e32 v28, 0x3fcc422a, v28
	v_mul_f32_e32 v26, 0xbfb8aa3b, v26
	v_exp_f32_e32 v6, v6
	v_mul_f32_e32 v29, 0x3d372713, v24
	v_mul_f32_e32 v27, v23, v27
	v_fma_f32 v7, v22, v7, v22
	v_mul_f32_e32 v30, 0x3fcc422a, v30
	v_mul_f32_e32 v28, 0xbfb8aa3b, v28
	v_exp_f32_e32 v26, v26
	v_mul_f32_e32 v31, 0x3d372713, v25
	v_mul_f32_e32 v29, v24, v29
	v_fma_f32 v27, v23, v27, v23
	v_mul_f32_e32 v7, 0x3fcc422a, v7
	v_mul_f32_e32 v30, 0xbfb8aa3b, v30
	v_exp_f32_e32 v28, v28
	v_mul_f32_e32 v31, v25, v31
	v_fma_f32 v29, v24, v29, v24
	v_mul_f32_e32 v27, 0x3fcc422a, v27
	v_mul_f32_e32 v7, 0xbfb8aa3b, v7
	v_exp_f32_e32 v30, v30
	v_fma_f32 v31, v25, v31, v25
	v_mul_f32_e32 v29, 0x3fcc422a, v29
	v_mul_f32_e32 v27, 0xbfb8aa3b, v27
	v_exp_f32_e32 v7, v7
	v_add_f32_e32 v6, 1.0, v6
	v_mul_f32_e32 v31, 0x3fcc422a, v31
	v_mul_f32_e32 v29, 0xbfb8aa3b, v29
	v_exp_f32_e32 v27, v27
	v_add_f32_e32 v26, 1.0, v26
	v_rcp_f32_e32 v32, v6
	v_mul_f32_e32 v31, 0xbfb8aa3b, v31
	v_exp_f32_e32 v29, v29
	v_add_f32_e32 v28, 1.0, v28
	v_rcp_f32_e32 v26, v26
	v_exp_f32_e32 v31, v31
	v_add_f32_e32 v30, 1.0, v30
	v_rcp_f32_e32 v28, v28
	v_add_f32_e32 v7, 1.0, v7
	v_rcp_f32_e32 v30, v30
	v_add_f32_e32 v27, 1.0, v27
	v_rcp_f32_e32 v7, v7
	v_fma_f32 v6, v18, v32, 0
	v_add_f32_e32 v29, 1.0, v29
	v_rcp_f32_e32 v27, v27
	v_fmac_f32_e32 v6, v19, v26
	v_add_f32_e32 v31, 1.0, v31
	v_rcp_f32_e32 v29, v29
	v_fmac_f32_e32 v6, v20, v28
	v_rcp_f32_e32 v31, v31
	v_fmac_f32_e32 v6, v21, v30
	v_fmac_f32_e32 v6, v22, v7
	v_fmac_f32_e32 v6, v23, v27
	v_fmac_f32_e32 v6, v24, v29
	v_fmac_f32_e32 v6, v25, v31
	s_nop 1
	v_add_f32_dpp v6, v6, v6 row_shr:1 row_mask:0xf bank_mask:0xf bound_ctrl:0
	s_nop 1
	v_add_f32_dpp v6, v6, v6 row_shr:2 row_mask:0xf bank_mask:0xf bound_ctrl:0
	s_nop 1
	v_add_f32_dpp v6, v6, v6 row_shr:4 row_mask:0xf bank_mask:0xf bound_ctrl:0
	s_nop 1
	v_add_f32_dpp v6, v6, v6 row_shr:8 row_mask:0xf bank_mask:0xf bound_ctrl:0
	s_nop 1
	v_add_f32_dpp v6, v6, v6 row_bcast:15 row_mask:0xa bank_mask:0xf
	s_nop 1
	v_add_f32_dpp v6, v6, v6 row_bcast:31 row_mask:0xc bank_mask:0xf
	s_nop 1
	v_readlane_b32 s10, v6, 63
	s_nop 1
	v_mov_b32_e32 v6, s10
	v_mul_f32_e32 v6, 0x3b000000, v6
	v_fma_f32 v19, v19, v26, -v6
	v_fma_f32 v18, v18, v32, -v6
	v_mul_f32_e32 v19, v19, v19
	v_fma_f32 v20, v20, v28, -v6
	v_fmac_f32_e32 v19, v18, v18
	v_fma_f32 v21, v21, v30, -v6
	v_fmac_f32_e32 v19, v20, v20
	v_fma_f32 v7, v22, v7, -v6
	v_fmac_f32_e32 v19, v21, v21
	v_fma_f32 v22, v23, v27, -v6
	v_fmac_f32_e32 v19, v7, v7
	v_fma_f32 v23, v24, v29, -v6
	v_fmac_f32_e32 v19, v22, v22
	v_fmac_f32_e32 v19, v23, v23
	v_fma_f32 v7, v25, v31, -v6
	v_fmac_f32_e32 v19, v7, v7
	v_mov_b32_e32 v7, v19
	s_nop 1
	v_add_f32_dpp v7, v7, v7 row_shr:1 row_mask:0xf bank_mask:0xf bound_ctrl:0
	s_nop 1
	v_add_f32_dpp v7, v7, v7 row_shr:2 row_mask:0xf bank_mask:0xf bound_ctrl:0
	s_nop 1
	v_add_f32_dpp v7, v7, v7 row_shr:4 row_mask:0xf bank_mask:0xf bound_ctrl:0
	s_nop 1
	v_add_f32_dpp v7, v7, v7 row_shr:8 row_mask:0xf bank_mask:0xf bound_ctrl:0
	s_nop 1
	v_add_f32_dpp v7, v7, v7 row_bcast:15 row_mask:0xa bank_mask:0xf
	s_nop 1
	v_add_f32_dpp v7, v7, v7 row_bcast:31 row_mask:0xc bank_mask:0xf
	s_nop 1
	v_readlane_b32 s10, v7, 63
	s_nop 1
	v_mov_b32_e32 v7, s10
	v_mov_b32_e32 v18, 0
	s_and_saveexec_b64 s[56:57], s[42:43]
	s_cbranch_execz .LBB0_766
	s_waitcnt lgkmcnt(0)
	v_add_f32_e32 v7, v7, v18
	v_fmamk_f32 v7, v7, 0x3b000000, v194
	v_mul_f32_e32 v18, 0x4b800000, v7
	v_cmp_gt_f32_e32 vcc, s95, v7
	s_nop 1
	v_cndmask_b32_e32 v7, v7, v18, vcc
	v_rsq_f32_e32 v7, v7
	s_nop 0
	v_mul_f32_e32 v18, 0x45800000, v7
	v_cndmask_b32_e32 v7, v7, v18, vcc
	ds_write_b64 v17, v[6:7] offset:48
; DI float gelu_t(float x) { return x * sigm(1.5957691216057308f * (x + 0.044715f * x * x * x)); }
; DI void prep_a_prompt(LAS unsigned char* lds, const Params& P, int l, int unit) {
;     ...
;     for (int i = 0; i < 16; ++i) { const int t = wave * 16 + i; const float* p = P32 + (size_t)(row0 + t) * LDP + C_AV + lane * 8;
;         const f32x4 a = *(const f32x4*)p, bq = *(const f32x4*)(p + 4); float x[8];
; #pragma unroll
;         for (int e = 0; e < 4; ++e) { x[e] = gelu_t(a[e]); x[4 + e] = gelu_t(bq[e]); }
;         float s = 0.f;
; #pragma unroll
;         for (int e = 0; e < 8; ++e) s += x[e];
;         const float mean = wsum(s) * (1.f / 512.f); float d = 0.f;
; #pragma unroll
;         for (int e = 0; e < 8; ++e) d += (x[e] - mean) * (x[e] - mean);
;         const float var = wsum(d) * (1.f / 512.f);
;         if (lane == 0) { st[t * 2] = mean; st[t * 2 + 1] = rsqrtf(var + 1e-6f); } }
.LBB0_766:
	s_or_b64 exec, exec, s[56:57]
	s_mov_b64 s[6:7], 0x2e000
	v_lshl_add_u64 v[6:7], v[4:5], 0, s[6:7]
	v_add_co_u32_e32 v4, vcc, 0x2e000, v4
	s_nop 1
	v_addc_co_u32_e32 v5, vcc, 0, v5, vcc
	s_waitcnt lgkmcnt(0)
	s_waitcnt vmcnt(1)
	v_mov_b32_e32 v18, v112
	v_mov_b32_e32 v19, v113
	v_mov_b32_e32 v20, v114
	v_mov_b32_e32 v21, v115
	v_mul_f32_e32 v4, 0x3d372713, v18
	v_mul_f32_e32 v6, 0x3d372713, v19
	v_mul_f32_e32 v4, v18, v4
	v_mul_f32_e32 v26, 0x3d372713, v20
	v_mul_f32_e32 v6, v19, v6
	v_fma_f32 v4, v18, v4, v18
	v_mul_f32_e32 v28, 0x3d372713, v21
	v_mul_f32_e32 v26, v20, v26
	v_fma_f32 v6, v19, v6, v19
	v_mul_f32_e32 v4, 0x3fcc422a, v4
	s_waitcnt vmcnt(0)
	v_mov_b32_e32 v22, v116
	v_mov_b32_e32 v23, v117
	v_mov_b32_e32 v24, v118
	v_mov_b32_e32 v25, v119
	v_mul_f32_e32 v5, 0x3d372713, v22
	v_mul_f32_e32 v28, v21, v28
	v_fma_f32 v26, v20, v26, v20
	v_mul_f32_e32 v6, 0x3fcc422a, v6
	v_mul_f32_e32 v4, 0xbfb8aa3b, v4
	v_mul_f32_e32 v7, 0x3d372713, v23
	v_mul_f32_e32 v5, v22, v5
	v_fma_f32 v28, v21, v28, v21
	v_mul_f32_e32 v26, 0x3fcc422a, v26
	v_mul_f32_e32 v6, 0xbfb8aa3b, v6
	v_exp_f32_e32 v4, v4
	v_mul_f32_e32 v27, 0x3d372713, v24
	v_mul_f32_e32 v7, v23, v7
	v_fma_f32 v5, v22, v5, v22
	v_mul_f32_e32 v28, 0x3fcc422a, v28
	v_mul_f32_e32 v26, 0xbfb8aa3b, v26
	v_exp_f32_e32 v6, v6
	v_mul_f32_e32 v29, 0x3d372713, v25
	v_mul_f32_e32 v27, v24, v27
	v_fma_f32 v7, v23, v7, v23
	v_mul_f32_e32 v5, 0x3fcc422a, v5
	v_mul_f32_e32 v28, 0xbfb8aa3b, v28
	v_exp_f32_e32 v26, v26
	v_mul_f32_e32 v29, v25, v29
	v_fma_f32 v27, v24, v27, v24
	v_mul_f32_e32 v7, 0x3fcc422a, v7
	v_mul_f32_e32 v5, 0xbfb8aa3b, v5
	v_exp_f32_e32 v28, v28
	v_fma_f32 v29, v25, v29, v25
	v_mul_f32_e32 v27, 0x3fcc422a, v27
	v_mul_f32_e32 v7, 0xbfb8aa3b, v7
	v_exp_f32_e32 v5, v5
	v_add_f32_e32 v4, 1.0, v4
	v_mul_f32_e32 v29, 0x3fcc422a, v29
	v_mul_f32_e32 v27, 0xbfb8aa3b, v27
	v_exp_f32_e32 v7, v7
	v_add_f32_e32 v6, 1.0, v6
	v_rcp_f32_e32 v30, v4
	v_mul_f32_e32 v29, 0xbfb8aa3b, v29
	v_exp_f32_e32 v27, v27
	v_add_f32_e32 v26, 1.0, v26
	v_rcp_f32_e32 v6, v6
	v_exp_f32_e32 v29, v29
	v_add_f32_e32 v28, 1.0, v28
	v_rcp_f32_e32 v26, v26
	v_add_f32_e32 v5, 1.0, v5
	v_rcp_f32_e32 v28, v28
	v_add_f32_e32 v7, 1.0, v7
	v_rcp_f32_e32 v5, v5
	v_fma_f32 v4, v18, v30, 0
	v_add_f32_e32 v27, 1.0, v27
	v_rcp_f32_e32 v7, v7
	v_fmac_f32_e32 v4, v19, v6
	v_add_f32_e32 v29, 1.0, v29
	v_rcp_f32_e32 v27, v27
	v_fmac_f32_e32 v4, v20, v26
	v_rcp_f32_e32 v29, v29
	v_fmac_f32_e32 v4, v21, v28
	v_fmac_f32_e32 v4, v22, v5
	v_fmac_f32_e32 v4, v23, v7
	v_fmac_f32_e32 v4, v24, v27
	v_fmac_f32_e32 v4, v25, v29
	s_nop 1
	v_add_f32_dpp v4, v4, v4 row_shr:1 row_mask:0xf bank_mask:0xf bound_ctrl:0
	s_nop 1
	v_add_f32_dpp v4, v4, v4 row_shr:2 row_mask:0xf bank_mask:0xf bound_ctrl:0
	s_nop 1
	v_add_f32_dpp v4, v4, v4 row_shr:4 row_mask:0xf bank_mask:0xf bound_ctrl:0
	s_nop 1
	v_add_f32_dpp v4, v4, v4 row_shr:8 row_mask:0xf bank_mask:0xf bound_ctrl:0
	s_nop 1
	v_add_f32_dpp v4, v4, v4 row_bcast:15 row_mask:0xa bank_mask:0xf
	s_nop 1
	v_add_f32_dpp v4, v4, v4 row_bcast:31 row_mask:0xc bank_mask:0xf
	s_nop 1
	v_readlane_b32 s10, v4, 63
	s_nop 1
	v_mov_b32_e32 v4, s10
	v_mul_f32_e32 v4, 0x3b000000, v4
	v_fma_f32 v6, v19, v6, -v4
	v_fma_f32 v18, v18, v30, -v4
	v_mul_f32_e32 v6, v6, v6
	v_fma_f32 v19, v20, v26, -v4
	v_fmac_f32_e32 v6, v18, v18
	v_fma_f32 v20, v21, v28, -v4
	v_fmac_f32_e32 v6, v19, v19
	v_fma_f32 v5, v22, v5, -v4
	v_fmac_f32_e32 v6, v20, v20
	v_fma_f32 v7, v23, v7, -v4
	v_fmac_f32_e32 v6, v5, v5
	v_fma_f32 v21, v24, v27, -v4
	v_fmac_f32_e32 v6, v7, v7
	v_fmac_f32_e32 v6, v21, v21
	v_fma_f32 v5, v25, v29, -v4
	v_fmac_f32_e32 v6, v5, v5
	v_mov_b32_e32 v5, v6
	s_nop 1
	v_add_f32_dpp v5, v5, v5 row_shr:1 row_mask:0xf bank_mask:0xf bound_ctrl:0
	s_nop 1
	v_add_f32_dpp v5, v5, v5 row_shr:2 row_mask:0xf bank_mask:0xf bound_ctrl:0
	s_nop 1
	v_add_f32_dpp v5, v5, v5 row_shr:4 row_mask:0xf bank_mask:0xf bound_ctrl:0
	s_nop 1
	v_add_f32_dpp v5, v5, v5 row_shr:8 row_mask:0xf bank_mask:0xf bound_ctrl:0
	s_nop 1
	v_add_f32_dpp v5, v5, v5 row_bcast:15 row_mask:0xa bank_mask:0xf
	s_nop 1
	v_add_f32_dpp v5, v5, v5 row_bcast:31 row_mask:0xc bank_mask:0xf
	s_nop 1
	v_readlane_b32 s10, v5, 63
	s_nop 1
	v_mov_b32_e32 v5, s10
	v_mov_b32_e32 v6, 0
	s_and_saveexec_b64 s[56:57], s[42:43]
	s_cbranch_execz .LBB0_751
	s_waitcnt lgkmcnt(0)
	v_add_f32_e32 v5, v5, v6
	v_fmamk_f32 v5, v5, 0x3b000000, v194
	v_mul_f32_e32 v6, 0x4b800000, v5
	v_cmp_gt_f32_e32 vcc, s95, v5
	s_nop 1
	v_cndmask_b32_e32 v5, v5, v6, vcc
	v_rsq_f32_e32 v5, v5
	s_nop 0
	v_mul_f32_e32 v6, 0x45800000, v5
	v_cndmask_b32_e32 v5, v5, v6, vcc
	ds_write_b64 v17, v[4:5] offset:56
	s_branch .LBB0_751
